# FFN epilogue constants (conv weights, bias) now loaded before the epilogue barrier on the non-tail path
# speedup vs baseline: 1.0197x; 1.0024x over previous
.LBB0_1524:
	v_lshlrev_b64 v[194:195], 2, v[160:161]
	v_lshl_add_u64 v[162:163], s[18:19], 0, v[194:195]
	global_load_dwordx4 v[196:199], v[162:163], off
	global_load_dwordx4 v[200:203], v[162:163], off offset:16
	v_lshl_add_u64 v[250:251], s[24:25], 0, v[194:195]
	global_load_dwordx4 v[204:207], v[250:251], off
	global_load_dwordx4 v[208:211], v[250:251], off offset:16
	v_lshl_add_u64 v[162:163], s[26:27], 0, v[194:195]
	global_load_dwordx4 v[212:215], v[162:163], off
	global_load_dwordx4 v[216:219], v[162:163], off offset:16
	v_lshl_add_u64 v[250:251], s[6:7], 0, v[194:195]
	global_load_dwordx4 v[220:223], v[250:251], off
	global_load_dwordx4 v[224:227], v[250:251], off offset:16
	s_mov_b64 s[60:61], 0

.LBB0_1531:
	s_or_b64 exec, exec, s[4:5]
	s_waitcnt lgkmcnt(0)
	s_andn2_b64 vcc, exec, s[58:59]
	s_barrier
	s_cbranch_vccnz .LBB0_1539
	v_cmp_eq_u32_e32 vcc, 15, v166
	s_add_i32 s37, 0, 0x20400
	s_nop 1
	v_cndmask_b32_e64 v188, 0, 1, vcc
	v_or_b32_e32 v194, s73, v188
	v_or_b32_e32 v195, s72, v188
	v_lshlrev_b32_e32 v194, 9, v194
	v_lshlrev_b32_e32 v195, 9, v195
	v_add3_u32 v194, s37, v194, v189
	v_add3_u32 v195, s37, v195, v189
	ds_read_b128 v[228:231], v194
	ds_read_b128 v[236:239], v194 offset:16
	ds_read_b128 v[240:243], v195
	ds_read_b128 v[244:247], v195 offset:16
	v_add_u32_e32 v188, s20, v166
	s_lshl_b32 s37, s56, 8
	v_add_u32_e32 v194, s37, v188
	v_ashrrev_i32_e32 v195, 31, v194
	v_lshlrev_b64 v[194:195], 13, v[194:195]
	v_lshl_add_u64 v[162:163], s[14:15], 0, v[194:195]
	v_lshl_add_u64 v[162:163], v[160:161], 1, v[162:163]
	v_cmp_lt_i32_e32 vcc, 1, v166
	s_xor_b64 s[58:59], s[22:23], -1
	s_mov_b64 s[2:3], 0x20000
	s_mov_b64 s[4:5], 0xa0000
	v_mov_b32_e32 v232, 0x3dd2d3e7
	v_mov_b32_e32 v248, 1.0
	s_nop 1
	s_or_b64 s[58:59], s[58:59], vcc
	s_waitcnt vmcnt(0) lgkmcnt(0)
	v_mul_f32_dpp v122, v228, v204 row_ror:1 row_mask:0xf bank_mask:0xf
	v_mul_f32_dpp v168, v236, v208 row_ror:1 row_mask:0xf bank_mask:0xf
	v_mul_f32_dpp v126, v228, v196 row_ror:2 row_mask:0xf bank_mask:0xf
	v_mul_f32_dpp v172, v236, v200 row_ror:2 row_mask:0xf bank_mask:0xf
	v_mul_f32_dpp v123, v229, v205 row_ror:1 row_mask:0xf bank_mask:0xf
	v_mul_f32_dpp v169, v237, v209 row_ror:1 row_mask:0xf bank_mask:0xf
	v_mul_f32_dpp v127, v229, v197 row_ror:2 row_mask:0xf bank_mask:0xf
	v_mul_f32_dpp v173, v237, v201 row_ror:2 row_mask:0xf bank_mask:0xf
	v_mul_f32_dpp v124, v230, v206 row_ror:1 row_mask:0xf bank_mask:0xf
	v_mul_f32_dpp v170, v238, v210 row_ror:1 row_mask:0xf bank_mask:0xf
	v_mul_f32_dpp v128, v230, v198 row_ror:2 row_mask:0xf bank_mask:0xf
	v_mul_f32_dpp v174, v238, v202 row_ror:2 row_mask:0xf bank_mask:0xf
	v_mul_f32_dpp v125, v231, v207 row_ror:1 row_mask:0xf bank_mask:0xf
	v_mul_f32_dpp v171, v239, v211 row_ror:1 row_mask:0xf bank_mask:0xf
	v_mul_f32_dpp v129, v231, v199 row_ror:2 row_mask:0xf bank_mask:0xf
	v_mul_f32_dpp v175, v239, v203 row_ror:2 row_mask:0xf bank_mask:0xf
	v_pk_fma_f32 v[118:119], v[212:213], v[138:139], v[220:221]
	v_pk_fma_f32 v[164:165], v[216:217], v[52:53], v[224:225]
	v_pk_fma_f32 v[120:121], v[214:215], v[140:141], v[222:223]
	v_pk_fma_f32 v[166:167], v[218:219], v[54:55], v[226:227]
	v_mul_f32_dpp v122, v138, v204 row_shr:1 row_mask:0xf bank_mask:0xf
	v_mul_f32_dpp v168, v52, v208 row_shr:1 row_mask:0xf bank_mask:0xf
	v_mul_f32_dpp v126, v138, v196 row_shr:2 row_mask:0xf bank_mask:0xf
	v_mul_f32_dpp v172, v52, v200 row_shr:2 row_mask:0xf bank_mask:0xf
	v_mul_f32_dpp v123, v139, v205 row_shr:1 row_mask:0xf bank_mask:0xf
	v_mul_f32_dpp v169, v53, v209 row_shr:1 row_mask:0xf bank_mask:0xf
	v_mul_f32_dpp v127, v139, v197 row_shr:2 row_mask:0xf bank_mask:0xf
	v_mul_f32_dpp v173, v53, v201 row_shr:2 row_mask:0xf bank_mask:0xf
	v_mul_f32_dpp v124, v140, v206 row_shr:1 row_mask:0xf bank_mask:0xf
	v_mul_f32_dpp v170, v54, v210 row_shr:1 row_mask:0xf bank_mask:0xf
	v_mul_f32_dpp v128, v140, v198 row_shr:2 row_mask:0xf bank_mask:0xf
	v_mul_f32_dpp v174, v54, v202 row_shr:2 row_mask:0xf bank_mask:0xf
	v_mul_f32_dpp v125, v141, v207 row_shr:1 row_mask:0xf bank_mask:0xf
	v_mul_f32_dpp v171, v55, v211 row_shr:1 row_mask:0xf bank_mask:0xf
	v_mul_f32_dpp v129, v141, v199 row_shr:2 row_mask:0xf bank_mask:0xf
	v_mul_f32_dpp v175, v55, v203 row_shr:2 row_mask:0xf bank_mask:0xf
	v_pk_add_f32 v[118:119], v[118:119], v[122:123]
	v_pk_add_f32 v[164:165], v[164:165], v[168:169]
	v_pk_add_f32 v[120:121], v[120:121], v[124:125]
	v_pk_add_f32 v[166:167], v[166:167], v[170:171]
	v_pk_add_f32 v[118:119], v[118:119], v[126:127]
	v_pk_add_f32 v[164:165], v[164:165], v[172:173]
	v_pk_add_f32 v[120:121], v[120:121], v[128:129]
	v_pk_add_f32 v[166:167], v[166:167], v[174:175]
	v_pk_mul_f32 v[122:123], v[118:119], v[118:119]
	v_pk_mul_f32 v[168:169], v[164:165], v[164:165]
	v_pk_mul_f32 v[124:125], v[120:121], v[120:121]
	v_pk_mul_f32 v[170:171], v[166:167], v[166:167]
	v_pk_fma_f32 v[122:123], v[122:123], v[232:233], v[178:179] op_sel_hi:[1,0,0]
	v_pk_fma_f32 v[168:169], v[168:169], v[232:233], v[178:179] op_sel_hi:[1,0,0]
	v_pk_fma_f32 v[124:125], v[124:125], v[232:233], v[178:179] op_sel_hi:[1,0,0]
	v_pk_fma_f32 v[170:171], v[170:171], v[232:233], v[178:179] op_sel_hi:[1,0,0]
	v_pk_mul_f32 v[122:123], v[118:119], v[122:123] neg_lo:[0,1] neg_hi:[0,1]
	v_pk_mul_f32 v[168:169], v[164:165], v[168:169] neg_lo:[0,1] neg_hi:[0,1]
	v_pk_mul_f32 v[124:125], v[120:121], v[124:125] neg_lo:[0,1] neg_hi:[0,1]
	v_pk_mul_f32 v[170:171], v[166:167], v[170:171] neg_lo:[0,1] neg_hi:[0,1]
	v_exp_f32_e32 v126, v122
	v_exp_f32_e32 v172, v168
	v_exp_f32_e32 v127, v123
	v_exp_f32_e32 v173, v169
	v_exp_f32_e32 v128, v124
	v_exp_f32_e32 v174, v170
	v_exp_f32_e32 v129, v125
	v_exp_f32_e32 v175, v171
	v_pk_add_f32 v[126:127], v[126:127], v[248:249] op_sel_hi:[1,0]
	v_pk_add_f32 v[172:173], v[172:173], v[248:249] op_sel_hi:[1,0]
	v_pk_add_f32 v[128:129], v[128:129], v[248:249] op_sel_hi:[1,0]
	v_pk_add_f32 v[174:175], v[174:175], v[248:249] op_sel_hi:[1,0]
	v_rcp_f32_e32 v126, v126
	v_rcp_f32_e32 v172, v172
	v_rcp_f32_e32 v127, v127
	v_rcp_f32_e32 v173, v173
	v_rcp_f32_e32 v128, v128
	v_rcp_f32_e32 v174, v174
	v_rcp_f32_e32 v129, v129
	v_rcp_f32_e32 v175, v175
	v_pk_mul_f32 v[122:123], v[118:119], v[126:127]
	v_pk_mul_f32 v[168:169], v[164:165], v[172:173]
	v_pk_mul_f32 v[124:125], v[120:121], v[128:129]
	v_pk_mul_f32 v[170:171], v[166:167], v[174:175]
	v_pk_mul_f32 v[142:143], v[142:143], v[122:123]
	v_pk_mul_f32 v[60:61], v[60:61], v[168:169]
	v_pk_mul_f32 v[144:145], v[144:145], v[124:125]
	v_pk_mul_f32 v[62:63], v[62:63], v[170:171]
	v_cvt_pk_bf16_f32 v130, v142, v143
	v_cvt_pk_bf16_f32 v132, v60, v61
	v_cvt_pk_bf16_f32 v131, v144, v145
	v_cvt_pk_bf16_f32 v133, v62, v63
	s_and_saveexec_b64 s[38:39], s[58:59]
	global_store_dwordx4 v[162:163], v[130:133], off
	s_mov_b64 exec, s[38:39]
	v_lshl_add_u64 v[162:163], v[162:163], 0, s[2:3]
	v_mul_f32_dpp v122, v138, v204 row_ror:1 row_mask:0xf bank_mask:0xf
	v_mul_f32_dpp v168, v52, v208 row_ror:1 row_mask:0xf bank_mask:0xf
	v_mul_f32_dpp v126, v138, v196 row_ror:2 row_mask:0xf bank_mask:0xf
	v_mul_f32_dpp v172, v52, v200 row_ror:2 row_mask:0xf bank_mask:0xf
	v_mul_f32_dpp v123, v139, v205 row_ror:1 row_mask:0xf bank_mask:0xf
	v_mul_f32_dpp v169, v53, v209 row_ror:1 row_mask:0xf bank_mask:0xf
	v_mul_f32_dpp v127, v139, v197 row_ror:2 row_mask:0xf bank_mask:0xf
	v_mul_f32_dpp v173, v53, v201 row_ror:2 row_mask:0xf bank_mask:0xf
	v_mul_f32_dpp v124, v140, v206 row_ror:1 row_mask:0xf bank_mask:0xf
	v_mul_f32_dpp v170, v54, v210 row_ror:1 row_mask:0xf bank_mask:0xf
	v_mul_f32_dpp v128, v140, v198 row_ror:2 row_mask:0xf bank_mask:0xf
	v_mul_f32_dpp v174, v54, v202 row_ror:2 row_mask:0xf bank_mask:0xf
	v_mul_f32_dpp v125, v141, v207 row_ror:1 row_mask:0xf bank_mask:0xf
	v_mul_f32_dpp v171, v55, v211 row_ror:1 row_mask:0xf bank_mask:0xf
	v_mul_f32_dpp v129, v141, v199 row_ror:2 row_mask:0xf bank_mask:0xf
	v_mul_f32_dpp v175, v55, v203 row_ror:2 row_mask:0xf bank_mask:0xf
	v_pk_fma_f32 v[118:119], v[212:213], v[114:115], v[220:221]
	v_pk_fma_f32 v[164:165], v[216:217], v[48:49], v[224:225]
	v_pk_fma_f32 v[120:121], v[214:215], v[116:117], v[222:223]
	v_pk_fma_f32 v[166:167], v[218:219], v[50:51], v[226:227]
	v_mul_f32_dpp v122, v114, v204 row_shr:1 row_mask:0xf bank_mask:0xf
	v_mul_f32_dpp v168, v48, v208 row_shr:1 row_mask:0xf bank_mask:0xf
	v_mul_f32_dpp v126, v114, v196 row_shr:2 row_mask:0xf bank_mask:0xf
	v_mul_f32_dpp v172, v48, v200 row_shr:2 row_mask:0xf bank_mask:0xf
	v_mul_f32_dpp v123, v115, v205 row_shr:1 row_mask:0xf bank_mask:0xf
	v_mul_f32_dpp v169, v49, v209 row_shr:1 row_mask:0xf bank_mask:0xf
	v_mul_f32_dpp v127, v115, v197 row_shr:2 row_mask:0xf bank_mask:0xf
	v_mul_f32_dpp v173, v49, v201 row_shr:2 row_mask:0xf bank_mask:0xf
	v_mul_f32_dpp v124, v116, v206 row_shr:1 row_mask:0xf bank_mask:0xf
	v_mul_f32_dpp v170, v50, v210 row_shr:1 row_mask:0xf bank_mask:0xf
	v_mul_f32_dpp v128, v116, v198 row_shr:2 row_mask:0xf bank_mask:0xf
	v_mul_f32_dpp v174, v50, v202 row_shr:2 row_mask:0xf bank_mask:0xf
	v_mul_f32_dpp v125, v117, v207 row_shr:1 row_mask:0xf bank_mask:0xf
	v_mul_f32_dpp v171, v51, v211 row_shr:1 row_mask:0xf bank_mask:0xf
	v_mul_f32_dpp v129, v117, v199 row_shr:2 row_mask:0xf bank_mask:0xf
	v_mul_f32_dpp v175, v51, v203 row_shr:2 row_mask:0xf bank_mask:0xf
	v_pk_add_f32 v[118:119], v[118:119], v[122:123]
	v_pk_add_f32 v[164:165], v[164:165], v[168:169]
	v_pk_add_f32 v[120:121], v[120:121], v[124:125]
	v_pk_add_f32 v[166:167], v[166:167], v[170:171]
	v_pk_add_f32 v[118:119], v[118:119], v[126:127]
	v_pk_add_f32 v[164:165], v[164:165], v[172:173]
	v_pk_add_f32 v[120:121], v[120:121], v[128:129]
	v_pk_add_f32 v[166:167], v[166:167], v[174:175]
	v_pk_mul_f32 v[122:123], v[118:119], v[118:119]
	v_pk_mul_f32 v[168:169], v[164:165], v[164:165]
	v_pk_mul_f32 v[124:125], v[120:121], v[120:121]
	v_pk_mul_f32 v[170:171], v[166:167], v[166:167]
	v_pk_fma_f32 v[122:123], v[122:123], v[232:233], v[178:179] op_sel_hi:[1,0,0]
	v_pk_fma_f32 v[168:169], v[168:169], v[232:233], v[178:179] op_sel_hi:[1,0,0]
	v_pk_fma_f32 v[124:125], v[124:125], v[232:233], v[178:179] op_sel_hi:[1,0,0]
	v_pk_fma_f32 v[170:171], v[170:171], v[232:233], v[178:179] op_sel_hi:[1,0,0]
	v_pk_mul_f32 v[122:123], v[118:119], v[122:123] neg_lo:[0,1] neg_hi:[0,1]
	v_pk_mul_f32 v[168:169], v[164:165], v[168:169] neg_lo:[0,1] neg_hi:[0,1]
	v_pk_mul_f32 v[124:125], v[120:121], v[124:125] neg_lo:[0,1] neg_hi:[0,1]
	v_pk_mul_f32 v[170:171], v[166:167], v[170:171] neg_lo:[0,1] neg_hi:[0,1]
	v_exp_f32_e32 v126, v122
	v_exp_f32_e32 v172, v168
	v_exp_f32_e32 v127, v123
	v_exp_f32_e32 v173, v169
	v_exp_f32_e32 v128, v124
	v_exp_f32_e32 v174, v170
	v_exp_f32_e32 v129, v125
	v_exp_f32_e32 v175, v171
	v_pk_add_f32 v[126:127], v[126:127], v[248:249] op_sel_hi:[1,0]
	v_pk_add_f32 v[172:173], v[172:173], v[248:249] op_sel_hi:[1,0]
	v_pk_add_f32 v[128:129], v[128:129], v[248:249] op_sel_hi:[1,0]
	v_pk_add_f32 v[174:175], v[174:175], v[248:249] op_sel_hi:[1,0]
	v_rcp_f32_e32 v126, v126
	v_rcp_f32_e32 v172, v172
	v_rcp_f32_e32 v127, v127
	v_rcp_f32_e32 v173, v173
	v_rcp_f32_e32 v128, v128
	v_rcp_f32_e32 v174, v174
	v_rcp_f32_e32 v129, v129
	v_rcp_f32_e32 v175, v175
	v_pk_mul_f32 v[122:123], v[118:119], v[126:127]
	v_pk_mul_f32 v[168:169], v[164:165], v[172:173]
	v_pk_mul_f32 v[124:125], v[120:121], v[128:129]
	v_pk_mul_f32 v[170:171], v[166:167], v[174:175]
	v_pk_mul_f32 v[134:135], v[134:135], v[122:123]
	v_pk_mul_f32 v[56:57], v[56:57], v[168:169]
	v_pk_mul_f32 v[136:137], v[136:137], v[124:125]
	v_pk_mul_f32 v[58:59], v[58:59], v[170:171]
	v_cvt_pk_bf16_f32 v190, v134, v135
	v_cvt_pk_bf16_f32 v192, v56, v57
	v_cvt_pk_bf16_f32 v191, v136, v137
	v_cvt_pk_bf16_f32 v193, v58, v59
	global_store_dwordx4 v[162:163], v[190:193], off
	v_lshl_add_u64 v[162:163], v[162:163], 0, s[2:3]
	v_mul_f32_dpp v122, v114, v204 row_ror:1 row_mask:0xf bank_mask:0xf
	v_mul_f32_dpp v168, v48, v208 row_ror:1 row_mask:0xf bank_mask:0xf
	v_mul_f32_dpp v126, v114, v196 row_ror:2 row_mask:0xf bank_mask:0xf
	v_mul_f32_dpp v172, v48, v200 row_ror:2 row_mask:0xf bank_mask:0xf
	v_mul_f32_dpp v123, v115, v205 row_ror:1 row_mask:0xf bank_mask:0xf
	v_mul_f32_dpp v169, v49, v209 row_ror:1 row_mask:0xf bank_mask:0xf
	v_mul_f32_dpp v127, v115, v197 row_ror:2 row_mask:0xf bank_mask:0xf
	v_mul_f32_dpp v173, v49, v201 row_ror:2 row_mask:0xf bank_mask:0xf
	v_mul_f32_dpp v124, v116, v206 row_ror:1 row_mask:0xf bank_mask:0xf
	v_mul_f32_dpp v170, v50, v210 row_ror:1 row_mask:0xf bank_mask:0xf
	v_mul_f32_dpp v128, v116, v198 row_ror:2 row_mask:0xf bank_mask:0xf
	v_mul_f32_dpp v174, v50, v202 row_ror:2 row_mask:0xf bank_mask:0xf
	v_mul_f32_dpp v125, v117, v207 row_ror:1 row_mask:0xf bank_mask:0xf
	v_mul_f32_dpp v171, v51, v211 row_ror:1 row_mask:0xf bank_mask:0xf
	v_mul_f32_dpp v129, v117, v199 row_ror:2 row_mask:0xf bank_mask:0xf
	v_mul_f32_dpp v175, v51, v203 row_ror:2 row_mask:0xf bank_mask:0xf
	v_pk_fma_f32 v[118:119], v[212:213], v[106:107], v[220:221]
	v_pk_fma_f32 v[164:165], v[216:217], v[40:41], v[224:225]
	v_pk_fma_f32 v[120:121], v[214:215], v[108:109], v[222:223]
	v_pk_fma_f32 v[166:167], v[218:219], v[42:43], v[226:227]
	v_mul_f32_dpp v122, v106, v204 row_shr:1 row_mask:0xf bank_mask:0xf
	v_mul_f32_dpp v168, v40, v208 row_shr:1 row_mask:0xf bank_mask:0xf
	v_mul_f32_dpp v126, v106, v196 row_shr:2 row_mask:0xf bank_mask:0xf
	v_mul_f32_dpp v172, v40, v200 row_shr:2 row_mask:0xf bank_mask:0xf
	v_mul_f32_dpp v123, v107, v205 row_shr:1 row_mask:0xf bank_mask:0xf
	v_mul_f32_dpp v169, v41, v209 row_shr:1 row_mask:0xf bank_mask:0xf
	v_mul_f32_dpp v127, v107, v197 row_shr:2 row_mask:0xf bank_mask:0xf
	v_mul_f32_dpp v173, v41, v201 row_shr:2 row_mask:0xf bank_mask:0xf
	v_mul_f32_dpp v124, v108, v206 row_shr:1 row_mask:0xf bank_mask:0xf
	v_mul_f32_dpp v170, v42, v210 row_shr:1 row_mask:0xf bank_mask:0xf
	v_mul_f32_dpp v128, v108, v198 row_shr:2 row_mask:0xf bank_mask:0xf
	v_mul_f32_dpp v174, v42, v202 row_shr:2 row_mask:0xf bank_mask:0xf
	v_mul_f32_dpp v125, v109, v207 row_shr:1 row_mask:0xf bank_mask:0xf
	v_mul_f32_dpp v171, v43, v211 row_shr:1 row_mask:0xf bank_mask:0xf
	v_mul_f32_dpp v129, v109, v199 row_shr:2 row_mask:0xf bank_mask:0xf
	v_mul_f32_dpp v175, v43, v203 row_shr:2 row_mask:0xf bank_mask:0xf
	v_pk_add_f32 v[118:119], v[118:119], v[122:123]
	v_pk_add_f32 v[164:165], v[164:165], v[168:169]
	v_pk_add_f32 v[120:121], v[120:121], v[124:125]
	v_pk_add_f32 v[166:167], v[166:167], v[170:171]
	v_pk_add_f32 v[118:119], v[118:119], v[126:127]
	v_pk_add_f32 v[164:165], v[164:165], v[172:173]
	v_pk_add_f32 v[120:121], v[120:121], v[128:129]
	v_pk_add_f32 v[166:167], v[166:167], v[174:175]
	v_pk_mul_f32 v[122:123], v[118:119], v[118:119]
	v_pk_mul_f32 v[168:169], v[164:165], v[164:165]
	v_pk_mul_f32 v[124:125], v[120:121], v[120:121]
	v_pk_mul_f32 v[170:171], v[166:167], v[166:167]
	v_pk_fma_f32 v[122:123], v[122:123], v[232:233], v[178:179] op_sel_hi:[1,0,0]
	v_pk_fma_f32 v[168:169], v[168:169], v[232:233], v[178:179] op_sel_hi:[1,0,0]
	v_pk_fma_f32 v[124:125], v[124:125], v[232:233], v[178:179] op_sel_hi:[1,0,0]
	v_pk_fma_f32 v[170:171], v[170:171], v[232:233], v[178:179] op_sel_hi:[1,0,0]
	v_pk_mul_f32 v[122:123], v[118:119], v[122:123] neg_lo:[0,1] neg_hi:[0,1]
	v_pk_mul_f32 v[168:169], v[164:165], v[168:169] neg_lo:[0,1] neg_hi:[0,1]
	v_pk_mul_f32 v[124:125], v[120:121], v[124:125] neg_lo:[0,1] neg_hi:[0,1]
	v_pk_mul_f32 v[170:171], v[166:167], v[170:171] neg_lo:[0,1] neg_hi:[0,1]
	v_exp_f32_e32 v126, v122
	v_exp_f32_e32 v172, v168
	v_exp_f32_e32 v127, v123
	v_exp_f32_e32 v173, v169
	v_exp_f32_e32 v128, v124
	v_exp_f32_e32 v174, v170
	v_exp_f32_e32 v129, v125
	v_exp_f32_e32 v175, v171
	v_pk_add_f32 v[126:127], v[126:127], v[248:249] op_sel_hi:[1,0]
	v_pk_add_f32 v[172:173], v[172:173], v[248:249] op_sel_hi:[1,0]
	v_pk_add_f32 v[128:129], v[128:129], v[248:249] op_sel_hi:[1,0]
	v_pk_add_f32 v[174:175], v[174:175], v[248:249] op_sel_hi:[1,0]
	v_rcp_f32_e32 v126, v126
	v_rcp_f32_e32 v172, v172
	v_rcp_f32_e32 v127, v127
	v_rcp_f32_e32 v173, v173
	v_rcp_f32_e32 v128, v128
	v_rcp_f32_e32 v174, v174
	v_rcp_f32_e32 v129, v129
	v_rcp_f32_e32 v175, v175
	v_pk_mul_f32 v[122:123], v[118:119], v[126:127]
	v_pk_mul_f32 v[168:169], v[164:165], v[172:173]
	v_pk_mul_f32 v[124:125], v[120:121], v[128:129]
	v_pk_mul_f32 v[170:171], v[166:167], v[174:175]
	v_pk_mul_f32 v[110:111], v[110:111], v[122:123]
	v_pk_mul_f32 v[44:45], v[44:45], v[168:169]
	v_pk_mul_f32 v[112:113], v[112:113], v[124:125]
	v_pk_mul_f32 v[46:47], v[46:47], v[170:171]
	v_cvt_pk_bf16_f32 v130, v110, v111
	v_cvt_pk_bf16_f32 v132, v44, v45
	v_cvt_pk_bf16_f32 v131, v112, v113
	v_cvt_pk_bf16_f32 v133, v46, v47
	global_store_dwordx4 v[162:163], v[130:133], off
	v_lshl_add_u64 v[162:163], v[162:163], 0, s[2:3]
	v_mul_f32_dpp v122, v106, v204 row_ror:1 row_mask:0xf bank_mask:0xf
	v_mul_f32_dpp v168, v40, v208 row_ror:1 row_mask:0xf bank_mask:0xf
	v_mul_f32_dpp v126, v106, v196 row_ror:2 row_mask:0xf bank_mask:0xf
	v_mul_f32_dpp v172, v40, v200 row_ror:2 row_mask:0xf bank_mask:0xf
	v_mul_f32_dpp v123, v107, v205 row_ror:1 row_mask:0xf bank_mask:0xf
	v_mul_f32_dpp v169, v41, v209 row_ror:1 row_mask:0xf bank_mask:0xf
	v_mul_f32_dpp v127, v107, v197 row_ror:2 row_mask:0xf bank_mask:0xf
	v_mul_f32_dpp v173, v41, v201 row_ror:2 row_mask:0xf bank_mask:0xf
	v_mul_f32_dpp v124, v108, v206 row_ror:1 row_mask:0xf bank_mask:0xf
	v_mul_f32_dpp v170, v42, v210 row_ror:1 row_mask:0xf bank_mask:0xf
	v_mul_f32_dpp v128, v108, v198 row_ror:2 row_mask:0xf bank_mask:0xf
	v_mul_f32_dpp v174, v42, v202 row_ror:2 row_mask:0xf bank_mask:0xf
	v_mul_f32_dpp v125, v109, v207 row_ror:1 row_mask:0xf bank_mask:0xf
	v_mul_f32_dpp v171, v43, v211 row_ror:1 row_mask:0xf bank_mask:0xf
	v_mul_f32_dpp v129, v109, v199 row_ror:2 row_mask:0xf bank_mask:0xf
	v_mul_f32_dpp v175, v43, v203 row_ror:2 row_mask:0xf bank_mask:0xf
	v_pk_fma_f32 v[118:119], v[212:213], v[102:103], v[220:221]
	v_pk_fma_f32 v[164:165], v[216:217], v[36:37], v[224:225]
	v_pk_fma_f32 v[120:121], v[214:215], v[104:105], v[222:223]
	v_pk_fma_f32 v[166:167], v[218:219], v[38:39], v[226:227]
	v_mul_f32_dpp v122, v102, v204 row_shr:1 row_mask:0xf bank_mask:0xf
	v_mul_f32_dpp v168, v36, v208 row_shr:1 row_mask:0xf bank_mask:0xf
	v_mul_f32_dpp v126, v102, v196 row_shr:2 row_mask:0xf bank_mask:0xf
	v_mul_f32_dpp v172, v36, v200 row_shr:2 row_mask:0xf bank_mask:0xf
	v_mul_f32_dpp v123, v103, v205 row_shr:1 row_mask:0xf bank_mask:0xf
	v_mul_f32_dpp v169, v37, v209 row_shr:1 row_mask:0xf bank_mask:0xf
	v_mul_f32_dpp v127, v103, v197 row_shr:2 row_mask:0xf bank_mask:0xf
	v_mul_f32_dpp v173, v37, v201 row_shr:2 row_mask:0xf bank_mask:0xf
	v_mul_f32_dpp v124, v104, v206 row_shr:1 row_mask:0xf bank_mask:0xf
	v_mul_f32_dpp v170, v38, v210 row_shr:1 row_mask:0xf bank_mask:0xf
	v_mul_f32_dpp v128, v104, v198 row_shr:2 row_mask:0xf bank_mask:0xf
	v_mul_f32_dpp v174, v38, v202 row_shr:2 row_mask:0xf bank_mask:0xf
	v_mul_f32_dpp v125, v105, v207 row_shr:1 row_mask:0xf bank_mask:0xf
	v_mul_f32_dpp v171, v39, v211 row_shr:1 row_mask:0xf bank_mask:0xf
	v_mul_f32_dpp v129, v105, v199 row_shr:2 row_mask:0xf bank_mask:0xf
	v_mul_f32_dpp v175, v39, v203 row_shr:2 row_mask:0xf bank_mask:0xf
	v_pk_add_f32 v[118:119], v[118:119], v[122:123]
	v_pk_add_f32 v[164:165], v[164:165], v[168:169]
	v_pk_add_f32 v[120:121], v[120:121], v[124:125]
	v_pk_add_f32 v[166:167], v[166:167], v[170:171]
	v_pk_add_f32 v[118:119], v[118:119], v[126:127]
	v_pk_add_f32 v[164:165], v[164:165], v[172:173]
	v_pk_add_f32 v[120:121], v[120:121], v[128:129]
	v_pk_add_f32 v[166:167], v[166:167], v[174:175]
	v_pk_mul_f32 v[122:123], v[118:119], v[118:119]
	v_pk_mul_f32 v[168:169], v[164:165], v[164:165]
	v_pk_mul_f32 v[124:125], v[120:121], v[120:121]
	v_pk_mul_f32 v[170:171], v[166:167], v[166:167]
	v_pk_fma_f32 v[122:123], v[122:123], v[232:233], v[178:179] op_sel_hi:[1,0,0]
	v_pk_fma_f32 v[168:169], v[168:169], v[232:233], v[178:179] op_sel_hi:[1,0,0]
	v_pk_fma_f32 v[124:125], v[124:125], v[232:233], v[178:179] op_sel_hi:[1,0,0]
	v_pk_fma_f32 v[170:171], v[170:171], v[232:233], v[178:179] op_sel_hi:[1,0,0]
	v_pk_mul_f32 v[122:123], v[118:119], v[122:123] neg_lo:[0,1] neg_hi:[0,1]
	v_pk_mul_f32 v[168:169], v[164:165], v[168:169] neg_lo:[0,1] neg_hi:[0,1]
	v_pk_mul_f32 v[124:125], v[120:121], v[124:125] neg_lo:[0,1] neg_hi:[0,1]
	v_pk_mul_f32 v[170:171], v[166:167], v[170:171] neg_lo:[0,1] neg_hi:[0,1]
	v_exp_f32_e32 v126, v122
	v_exp_f32_e32 v172, v168
	v_exp_f32_e32 v127, v123
	v_exp_f32_e32 v173, v169
	v_exp_f32_e32 v128, v124
	v_exp_f32_e32 v174, v170
	v_exp_f32_e32 v129, v125
	v_exp_f32_e32 v175, v171
	v_pk_add_f32 v[126:127], v[126:127], v[248:249] op_sel_hi:[1,0]
	v_pk_add_f32 v[172:173], v[172:173], v[248:249] op_sel_hi:[1,0]
	v_pk_add_f32 v[128:129], v[128:129], v[248:249] op_sel_hi:[1,0]
	v_pk_add_f32 v[174:175], v[174:175], v[248:249] op_sel_hi:[1,0]
	v_rcp_f32_e32 v126, v126
	v_rcp_f32_e32 v172, v172
	v_rcp_f32_e32 v127, v127
	v_rcp_f32_e32 v173, v173
	v_rcp_f32_e32 v128, v128
	v_rcp_f32_e32 v174, v174
	v_rcp_f32_e32 v129, v129
	v_rcp_f32_e32 v175, v175
	v_pk_mul_f32 v[122:123], v[118:119], v[126:127]
	v_pk_mul_f32 v[168:169], v[164:165], v[172:173]
	v_pk_mul_f32 v[124:125], v[120:121], v[128:129]
	v_pk_mul_f32 v[170:171], v[166:167], v[174:175]
	v_pk_mul_f32 v[98:99], v[98:99], v[122:123]
	v_pk_mul_f32 v[32:33], v[32:33], v[168:169]
	v_pk_mul_f32 v[100:101], v[100:101], v[124:125]
	v_pk_mul_f32 v[34:35], v[34:35], v[170:171]
	v_cvt_pk_bf16_f32 v190, v98, v99
	v_cvt_pk_bf16_f32 v192, v32, v33
	v_cvt_pk_bf16_f32 v191, v100, v101
	v_cvt_pk_bf16_f32 v193, v34, v35
	global_store_dwordx4 v[162:163], v[190:193], off
	v_lshl_add_u64 v[162:163], v[162:163], 0, s[4:5]
	v_mul_f32_dpp v122, v240, v204 row_ror:1 row_mask:0xf bank_mask:0xf
	v_mul_f32_dpp v168, v244, v208 row_ror:1 row_mask:0xf bank_mask:0xf
	v_mul_f32_dpp v126, v240, v196 row_ror:2 row_mask:0xf bank_mask:0xf
	v_mul_f32_dpp v172, v244, v200 row_ror:2 row_mask:0xf bank_mask:0xf
	v_mul_f32_dpp v123, v241, v205 row_ror:1 row_mask:0xf bank_mask:0xf
	v_mul_f32_dpp v169, v245, v209 row_ror:1 row_mask:0xf bank_mask:0xf
	v_mul_f32_dpp v127, v241, v197 row_ror:2 row_mask:0xf bank_mask:0xf
	v_mul_f32_dpp v173, v245, v201 row_ror:2 row_mask:0xf bank_mask:0xf
	v_mul_f32_dpp v124, v242, v206 row_ror:1 row_mask:0xf bank_mask:0xf
	v_mul_f32_dpp v170, v246, v210 row_ror:1 row_mask:0xf bank_mask:0xf
	v_mul_f32_dpp v128, v242, v198 row_ror:2 row_mask:0xf bank_mask:0xf
	v_mul_f32_dpp v174, v246, v202 row_ror:2 row_mask:0xf bank_mask:0xf
	v_mul_f32_dpp v125, v243, v207 row_ror:1 row_mask:0xf bank_mask:0xf
	v_mul_f32_dpp v171, v247, v211 row_ror:1 row_mask:0xf bank_mask:0xf
	v_mul_f32_dpp v129, v243, v199 row_ror:2 row_mask:0xf bank_mask:0xf
	v_mul_f32_dpp v175, v247, v203 row_ror:2 row_mask:0xf bank_mask:0xf
	v_pk_fma_f32 v[118:119], v[212:213], v[88:89], v[220:221]
	v_pk_fma_f32 v[164:165], v[216:217], v[24:25], v[224:225]
	v_pk_fma_f32 v[120:121], v[214:215], v[90:91], v[222:223]
	v_pk_fma_f32 v[166:167], v[218:219], v[26:27], v[226:227]
	v_mul_f32_dpp v122, v88, v204 row_shr:1 row_mask:0xf bank_mask:0xf
	v_mul_f32_dpp v168, v24, v208 row_shr:1 row_mask:0xf bank_mask:0xf
	v_mul_f32_dpp v126, v88, v196 row_shr:2 row_mask:0xf bank_mask:0xf
	v_mul_f32_dpp v172, v24, v200 row_shr:2 row_mask:0xf bank_mask:0xf
	v_mul_f32_dpp v123, v89, v205 row_shr:1 row_mask:0xf bank_mask:0xf
	v_mul_f32_dpp v169, v25, v209 row_shr:1 row_mask:0xf bank_mask:0xf
	v_mul_f32_dpp v127, v89, v197 row_shr:2 row_mask:0xf bank_mask:0xf
	v_mul_f32_dpp v173, v25, v201 row_shr:2 row_mask:0xf bank_mask:0xf
	v_mul_f32_dpp v124, v90, v206 row_shr:1 row_mask:0xf bank_mask:0xf
	v_mul_f32_dpp v170, v26, v210 row_shr:1 row_mask:0xf bank_mask:0xf
	v_mul_f32_dpp v128, v90, v198 row_shr:2 row_mask:0xf bank_mask:0xf
	v_mul_f32_dpp v174, v26, v202 row_shr:2 row_mask:0xf bank_mask:0xf
	v_mul_f32_dpp v125, v91, v207 row_shr:1 row_mask:0xf bank_mask:0xf
	v_mul_f32_dpp v171, v27, v211 row_shr:1 row_mask:0xf bank_mask:0xf
	v_mul_f32_dpp v129, v91, v199 row_shr:2 row_mask:0xf bank_mask:0xf
	v_mul_f32_dpp v175, v27, v203 row_shr:2 row_mask:0xf bank_mask:0xf
	v_pk_add_f32 v[118:119], v[118:119], v[122:123]
	v_pk_add_f32 v[164:165], v[164:165], v[168:169]
	v_pk_add_f32 v[120:121], v[120:121], v[124:125]
	v_pk_add_f32 v[166:167], v[166:167], v[170:171]
	v_pk_add_f32 v[118:119], v[118:119], v[126:127]
	v_pk_add_f32 v[164:165], v[164:165], v[172:173]
	v_pk_add_f32 v[120:121], v[120:121], v[128:129]
	v_pk_add_f32 v[166:167], v[166:167], v[174:175]
	v_pk_mul_f32 v[122:123], v[118:119], v[118:119]
	v_pk_mul_f32 v[168:169], v[164:165], v[164:165]
	v_pk_mul_f32 v[124:125], v[120:121], v[120:121]
	v_pk_mul_f32 v[170:171], v[166:167], v[166:167]
	v_pk_fma_f32 v[122:123], v[122:123], v[232:233], v[178:179] op_sel_hi:[1,0,0]
	v_pk_fma_f32 v[168:169], v[168:169], v[232:233], v[178:179] op_sel_hi:[1,0,0]
	v_pk_fma_f32 v[124:125], v[124:125], v[232:233], v[178:179] op_sel_hi:[1,0,0]
	v_pk_fma_f32 v[170:171], v[170:171], v[232:233], v[178:179] op_sel_hi:[1,0,0]
	v_pk_mul_f32 v[122:123], v[118:119], v[122:123] neg_lo:[0,1] neg_hi:[0,1]
	v_pk_mul_f32 v[168:169], v[164:165], v[168:169] neg_lo:[0,1] neg_hi:[0,1]
	v_pk_mul_f32 v[124:125], v[120:121], v[124:125] neg_lo:[0,1] neg_hi:[0,1]
	v_pk_mul_f32 v[170:171], v[166:167], v[170:171] neg_lo:[0,1] neg_hi:[0,1]
	v_exp_f32_e32 v126, v122
	v_exp_f32_e32 v172, v168
	v_exp_f32_e32 v127, v123
	v_exp_f32_e32 v173, v169
	v_exp_f32_e32 v128, v124
	v_exp_f32_e32 v174, v170
	v_exp_f32_e32 v129, v125
	v_exp_f32_e32 v175, v171
	v_pk_add_f32 v[126:127], v[126:127], v[248:249] op_sel_hi:[1,0]
	v_pk_add_f32 v[172:173], v[172:173], v[248:249] op_sel_hi:[1,0]
	v_pk_add_f32 v[128:129], v[128:129], v[248:249] op_sel_hi:[1,0]
	v_pk_add_f32 v[174:175], v[174:175], v[248:249] op_sel_hi:[1,0]
	v_rcp_f32_e32 v126, v126
	v_rcp_f32_e32 v172, v172
	v_rcp_f32_e32 v127, v127
	v_rcp_f32_e32 v173, v173
	v_rcp_f32_e32 v128, v128
	v_rcp_f32_e32 v174, v174
	v_rcp_f32_e32 v129, v129
	v_rcp_f32_e32 v175, v175
	v_pk_mul_f32 v[122:123], v[118:119], v[126:127]
	v_pk_mul_f32 v[168:169], v[164:165], v[172:173]
	v_pk_mul_f32 v[124:125], v[120:121], v[128:129]
	v_pk_mul_f32 v[170:171], v[166:167], v[174:175]
	v_pk_mul_f32 v[92:93], v[92:93], v[122:123]
	v_pk_mul_f32 v[28:29], v[28:29], v[168:169]
	v_pk_mul_f32 v[94:95], v[94:95], v[124:125]
	v_pk_mul_f32 v[30:31], v[30:31], v[170:171]
	v_cvt_pk_bf16_f32 v130, v92, v93
	v_cvt_pk_bf16_f32 v132, v28, v29
	v_cvt_pk_bf16_f32 v131, v94, v95
	v_cvt_pk_bf16_f32 v133, v30, v31
	global_store_dwordx4 v[162:163], v[130:133], off
	v_lshl_add_u64 v[162:163], v[162:163], 0, s[2:3]
	v_mul_f32_dpp v122, v88, v204 row_ror:1 row_mask:0xf bank_mask:0xf
	v_mul_f32_dpp v168, v24, v208 row_ror:1 row_mask:0xf bank_mask:0xf
	v_mul_f32_dpp v126, v88, v196 row_ror:2 row_mask:0xf bank_mask:0xf
	v_mul_f32_dpp v172, v24, v200 row_ror:2 row_mask:0xf bank_mask:0xf
	v_mul_f32_dpp v123, v89, v205 row_ror:1 row_mask:0xf bank_mask:0xf
	v_mul_f32_dpp v169, v25, v209 row_ror:1 row_mask:0xf bank_mask:0xf
	v_mul_f32_dpp v127, v89, v197 row_ror:2 row_mask:0xf bank_mask:0xf
	v_mul_f32_dpp v173, v25, v201 row_ror:2 row_mask:0xf bank_mask:0xf
	v_mul_f32_dpp v124, v90, v206 row_ror:1 row_mask:0xf bank_mask:0xf
	v_mul_f32_dpp v170, v26, v210 row_ror:1 row_mask:0xf bank_mask:0xf
	v_mul_f32_dpp v128, v90, v198 row_ror:2 row_mask:0xf bank_mask:0xf
	v_mul_f32_dpp v174, v26, v202 row_ror:2 row_mask:0xf bank_mask:0xf
	v_mul_f32_dpp v125, v91, v207 row_ror:1 row_mask:0xf bank_mask:0xf
	v_mul_f32_dpp v171, v27, v211 row_ror:1 row_mask:0xf bank_mask:0xf
	v_mul_f32_dpp v129, v91, v199 row_ror:2 row_mask:0xf bank_mask:0xf
	v_mul_f32_dpp v175, v27, v203 row_ror:2 row_mask:0xf bank_mask:0xf
	v_pk_fma_f32 v[118:119], v[212:213], v[80:81], v[220:221]
	v_pk_fma_f32 v[164:165], v[216:217], v[16:17], v[224:225]
	v_pk_fma_f32 v[120:121], v[214:215], v[82:83], v[222:223]
	v_pk_fma_f32 v[166:167], v[218:219], v[18:19], v[226:227]
	v_mul_f32_dpp v122, v80, v204 row_shr:1 row_mask:0xf bank_mask:0xf
	v_mul_f32_dpp v168, v16, v208 row_shr:1 row_mask:0xf bank_mask:0xf
	v_mul_f32_dpp v126, v80, v196 row_shr:2 row_mask:0xf bank_mask:0xf
	v_mul_f32_dpp v172, v16, v200 row_shr:2 row_mask:0xf bank_mask:0xf
	v_mul_f32_dpp v123, v81, v205 row_shr:1 row_mask:0xf bank_mask:0xf
	v_mul_f32_dpp v169, v17, v209 row_shr:1 row_mask:0xf bank_mask:0xf
	v_mul_f32_dpp v127, v81, v197 row_shr:2 row_mask:0xf bank_mask:0xf
	v_mul_f32_dpp v173, v17, v201 row_shr:2 row_mask:0xf bank_mask:0xf
	v_mul_f32_dpp v124, v82, v206 row_shr:1 row_mask:0xf bank_mask:0xf
	v_mul_f32_dpp v170, v18, v210 row_shr:1 row_mask:0xf bank_mask:0xf
	v_mul_f32_dpp v128, v82, v198 row_shr:2 row_mask:0xf bank_mask:0xf
	v_mul_f32_dpp v174, v18, v202 row_shr:2 row_mask:0xf bank_mask:0xf
	v_mul_f32_dpp v125, v83, v207 row_shr:1 row_mask:0xf bank_mask:0xf
	v_mul_f32_dpp v171, v19, v211 row_shr:1 row_mask:0xf bank_mask:0xf
	v_mul_f32_dpp v129, v83, v199 row_shr:2 row_mask:0xf bank_mask:0xf
	v_mul_f32_dpp v175, v19, v203 row_shr:2 row_mask:0xf bank_mask:0xf
	v_pk_add_f32 v[118:119], v[118:119], v[122:123]
	v_pk_add_f32 v[164:165], v[164:165], v[168:169]
	v_pk_add_f32 v[120:121], v[120:121], v[124:125]
	v_pk_add_f32 v[166:167], v[166:167], v[170:171]
	v_pk_add_f32 v[118:119], v[118:119], v[126:127]
	v_pk_add_f32 v[164:165], v[164:165], v[172:173]
	v_pk_add_f32 v[120:121], v[120:121], v[128:129]
	v_pk_add_f32 v[166:167], v[166:167], v[174:175]
	v_pk_mul_f32 v[122:123], v[118:119], v[118:119]
	v_pk_mul_f32 v[168:169], v[164:165], v[164:165]
	v_pk_mul_f32 v[124:125], v[120:121], v[120:121]
	v_pk_mul_f32 v[170:171], v[166:167], v[166:167]
	v_pk_fma_f32 v[122:123], v[122:123], v[232:233], v[178:179] op_sel_hi:[1,0,0]
	v_pk_fma_f32 v[168:169], v[168:169], v[232:233], v[178:179] op_sel_hi:[1,0,0]
	v_pk_fma_f32 v[124:125], v[124:125], v[232:233], v[178:179] op_sel_hi:[1,0,0]
	v_pk_fma_f32 v[170:171], v[170:171], v[232:233], v[178:179] op_sel_hi:[1,0,0]
	v_pk_mul_f32 v[122:123], v[118:119], v[122:123] neg_lo:[0,1] neg_hi:[0,1]
	v_pk_mul_f32 v[168:169], v[164:165], v[168:169] neg_lo:[0,1] neg_hi:[0,1]
	v_pk_mul_f32 v[124:125], v[120:121], v[124:125] neg_lo:[0,1] neg_hi:[0,1]
	v_pk_mul_f32 v[170:171], v[166:167], v[170:171] neg_lo:[0,1] neg_hi:[0,1]
	v_exp_f32_e32 v126, v122
	v_exp_f32_e32 v172, v168
	v_exp_f32_e32 v127, v123
	v_exp_f32_e32 v173, v169
	v_exp_f32_e32 v128, v124
	v_exp_f32_e32 v174, v170
	v_exp_f32_e32 v129, v125
	v_exp_f32_e32 v175, v171
	v_pk_add_f32 v[126:127], v[126:127], v[248:249] op_sel_hi:[1,0]
	v_pk_add_f32 v[172:173], v[172:173], v[248:249] op_sel_hi:[1,0]
	v_pk_add_f32 v[128:129], v[128:129], v[248:249] op_sel_hi:[1,0]
	v_pk_add_f32 v[174:175], v[174:175], v[248:249] op_sel_hi:[1,0]
	v_rcp_f32_e32 v126, v126
	v_rcp_f32_e32 v172, v172
	v_rcp_f32_e32 v127, v127
	v_rcp_f32_e32 v173, v173
	v_rcp_f32_e32 v128, v128
	v_rcp_f32_e32 v174, v174
	v_rcp_f32_e32 v129, v129
	v_rcp_f32_e32 v175, v175
	v_pk_mul_f32 v[122:123], v[118:119], v[126:127]
	v_pk_mul_f32 v[168:169], v[164:165], v[172:173]
	v_pk_mul_f32 v[124:125], v[120:121], v[128:129]
	v_pk_mul_f32 v[170:171], v[166:167], v[174:175]
	v_pk_mul_f32 v[84:85], v[84:85], v[122:123]
	v_pk_mul_f32 v[20:21], v[20:21], v[168:169]
	v_pk_mul_f32 v[86:87], v[86:87], v[124:125]
	v_pk_mul_f32 v[22:23], v[22:23], v[170:171]
	v_cvt_pk_bf16_f32 v190, v84, v85
	v_cvt_pk_bf16_f32 v192, v20, v21
	v_cvt_pk_bf16_f32 v191, v86, v87
	v_cvt_pk_bf16_f32 v193, v22, v23
	global_store_dwordx4 v[162:163], v[190:193], off
	v_lshl_add_u64 v[162:163], v[162:163], 0, s[2:3]
	v_mul_f32_dpp v122, v80, v204 row_ror:1 row_mask:0xf bank_mask:0xf
	v_mul_f32_dpp v168, v16, v208 row_ror:1 row_mask:0xf bank_mask:0xf
	v_mul_f32_dpp v126, v80, v196 row_ror:2 row_mask:0xf bank_mask:0xf
	v_mul_f32_dpp v172, v16, v200 row_ror:2 row_mask:0xf bank_mask:0xf
	v_mul_f32_dpp v123, v81, v205 row_ror:1 row_mask:0xf bank_mask:0xf
	v_mul_f32_dpp v169, v17, v209 row_ror:1 row_mask:0xf bank_mask:0xf
	v_mul_f32_dpp v127, v81, v197 row_ror:2 row_mask:0xf bank_mask:0xf
	v_mul_f32_dpp v173, v17, v201 row_ror:2 row_mask:0xf bank_mask:0xf
	v_mul_f32_dpp v124, v82, v206 row_ror:1 row_mask:0xf bank_mask:0xf
	v_mul_f32_dpp v170, v18, v210 row_ror:1 row_mask:0xf bank_mask:0xf
	v_mul_f32_dpp v128, v82, v198 row_ror:2 row_mask:0xf bank_mask:0xf
	v_mul_f32_dpp v174, v18, v202 row_ror:2 row_mask:0xf bank_mask:0xf
	v_mul_f32_dpp v125, v83, v207 row_ror:1 row_mask:0xf bank_mask:0xf
	v_mul_f32_dpp v171, v19, v211 row_ror:1 row_mask:0xf bank_mask:0xf
	v_mul_f32_dpp v129, v83, v199 row_ror:2 row_mask:0xf bank_mask:0xf
	v_mul_f32_dpp v175, v19, v203 row_ror:2 row_mask:0xf bank_mask:0xf
	v_pk_fma_f32 v[118:119], v[212:213], v[72:73], v[220:221]
	v_pk_fma_f32 v[164:165], v[216:217], v[8:9], v[224:225]
	v_pk_fma_f32 v[120:121], v[214:215], v[74:75], v[222:223]
	v_pk_fma_f32 v[166:167], v[218:219], v[10:11], v[226:227]
	v_mul_f32_dpp v122, v72, v204 row_shr:1 row_mask:0xf bank_mask:0xf
	v_mul_f32_dpp v168, v8, v208 row_shr:1 row_mask:0xf bank_mask:0xf
	v_mul_f32_dpp v126, v72, v196 row_shr:2 row_mask:0xf bank_mask:0xf
	v_mul_f32_dpp v172, v8, v200 row_shr:2 row_mask:0xf bank_mask:0xf
	v_mul_f32_dpp v123, v73, v205 row_shr:1 row_mask:0xf bank_mask:0xf
	v_mul_f32_dpp v169, v9, v209 row_shr:1 row_mask:0xf bank_mask:0xf
	v_mul_f32_dpp v127, v73, v197 row_shr:2 row_mask:0xf bank_mask:0xf
	v_mul_f32_dpp v173, v9, v201 row_shr:2 row_mask:0xf bank_mask:0xf
	v_mul_f32_dpp v124, v74, v206 row_shr:1 row_mask:0xf bank_mask:0xf
	v_mul_f32_dpp v170, v10, v210 row_shr:1 row_mask:0xf bank_mask:0xf
	v_mul_f32_dpp v128, v74, v198 row_shr:2 row_mask:0xf bank_mask:0xf
	v_mul_f32_dpp v174, v10, v202 row_shr:2 row_mask:0xf bank_mask:0xf
	v_mul_f32_dpp v125, v75, v207 row_shr:1 row_mask:0xf bank_mask:0xf
	v_mul_f32_dpp v171, v11, v211 row_shr:1 row_mask:0xf bank_mask:0xf
	v_mul_f32_dpp v129, v75, v199 row_shr:2 row_mask:0xf bank_mask:0xf
	v_mul_f32_dpp v175, v11, v203 row_shr:2 row_mask:0xf bank_mask:0xf
	v_pk_add_f32 v[118:119], v[118:119], v[122:123]
	v_pk_add_f32 v[164:165], v[164:165], v[168:169]
	v_pk_add_f32 v[120:121], v[120:121], v[124:125]
	v_pk_add_f32 v[166:167], v[166:167], v[170:171]
	v_pk_add_f32 v[118:119], v[118:119], v[126:127]
	v_pk_add_f32 v[164:165], v[164:165], v[172:173]
	v_pk_add_f32 v[120:121], v[120:121], v[128:129]
	v_pk_add_f32 v[166:167], v[166:167], v[174:175]
	v_pk_mul_f32 v[122:123], v[118:119], v[118:119]
	v_pk_mul_f32 v[168:169], v[164:165], v[164:165]
	v_pk_mul_f32 v[124:125], v[120:121], v[120:121]
	v_pk_mul_f32 v[170:171], v[166:167], v[166:167]
	v_pk_fma_f32 v[122:123], v[122:123], v[232:233], v[178:179] op_sel_hi:[1,0,0]
	v_pk_fma_f32 v[168:169], v[168:169], v[232:233], v[178:179] op_sel_hi:[1,0,0]
	v_pk_fma_f32 v[124:125], v[124:125], v[232:233], v[178:179] op_sel_hi:[1,0,0]
	v_pk_fma_f32 v[170:171], v[170:171], v[232:233], v[178:179] op_sel_hi:[1,0,0]
	v_pk_mul_f32 v[122:123], v[118:119], v[122:123] neg_lo:[0,1] neg_hi:[0,1]
	v_pk_mul_f32 v[168:169], v[164:165], v[168:169] neg_lo:[0,1] neg_hi:[0,1]
	v_pk_mul_f32 v[124:125], v[120:121], v[124:125] neg_lo:[0,1] neg_hi:[0,1]
	v_pk_mul_f32 v[170:171], v[166:167], v[170:171] neg_lo:[0,1] neg_hi:[0,1]
	v_exp_f32_e32 v126, v122
	v_exp_f32_e32 v172, v168
	v_exp_f32_e32 v127, v123
	v_exp_f32_e32 v173, v169
	v_exp_f32_e32 v128, v124
	v_exp_f32_e32 v174, v170
	v_exp_f32_e32 v129, v125
	v_exp_f32_e32 v175, v171
	v_pk_add_f32 v[126:127], v[126:127], v[248:249] op_sel_hi:[1,0]
	v_pk_add_f32 v[172:173], v[172:173], v[248:249] op_sel_hi:[1,0]
	v_pk_add_f32 v[128:129], v[128:129], v[248:249] op_sel_hi:[1,0]
	v_pk_add_f32 v[174:175], v[174:175], v[248:249] op_sel_hi:[1,0]
	v_rcp_f32_e32 v126, v126
	v_rcp_f32_e32 v172, v172
	v_rcp_f32_e32 v127, v127
	v_rcp_f32_e32 v173, v173
	v_rcp_f32_e32 v128, v128
	v_rcp_f32_e32 v174, v174
	v_rcp_f32_e32 v129, v129
	v_rcp_f32_e32 v175, v175
	v_pk_mul_f32 v[122:123], v[118:119], v[126:127]
	v_pk_mul_f32 v[168:169], v[164:165], v[172:173]
	v_pk_mul_f32 v[124:125], v[120:121], v[128:129]
	v_pk_mul_f32 v[170:171], v[166:167], v[174:175]
	v_pk_mul_f32 v[76:77], v[76:77], v[122:123]
	v_pk_mul_f32 v[12:13], v[12:13], v[168:169]
	v_pk_mul_f32 v[78:79], v[78:79], v[124:125]
	v_pk_mul_f32 v[14:15], v[14:15], v[170:171]
	v_cvt_pk_bf16_f32 v130, v76, v77
	v_cvt_pk_bf16_f32 v132, v12, v13
	v_cvt_pk_bf16_f32 v131, v78, v79
	v_cvt_pk_bf16_f32 v133, v14, v15
	global_store_dwordx4 v[162:163], v[130:133], off
	v_lshl_add_u64 v[162:163], v[162:163], 0, s[2:3]
	v_mul_f32_dpp v122, v72, v204 row_ror:1 row_mask:0xf bank_mask:0xf
	v_mul_f32_dpp v168, v8, v208 row_ror:1 row_mask:0xf bank_mask:0xf
	v_mul_f32_dpp v126, v72, v196 row_ror:2 row_mask:0xf bank_mask:0xf
	v_mul_f32_dpp v172, v8, v200 row_ror:2 row_mask:0xf bank_mask:0xf
	v_mul_f32_dpp v123, v73, v205 row_ror:1 row_mask:0xf bank_mask:0xf
	v_mul_f32_dpp v169, v9, v209 row_ror:1 row_mask:0xf bank_mask:0xf
	v_mul_f32_dpp v127, v73, v197 row_ror:2 row_mask:0xf bank_mask:0xf
	v_mul_f32_dpp v173, v9, v201 row_ror:2 row_mask:0xf bank_mask:0xf
	v_mul_f32_dpp v124, v74, v206 row_ror:1 row_mask:0xf bank_mask:0xf
	v_mul_f32_dpp v170, v10, v210 row_ror:1 row_mask:0xf bank_mask:0xf
	v_mul_f32_dpp v128, v74, v198 row_ror:2 row_mask:0xf bank_mask:0xf
	v_mul_f32_dpp v174, v10, v202 row_ror:2 row_mask:0xf bank_mask:0xf
	v_mul_f32_dpp v125, v75, v207 row_ror:1 row_mask:0xf bank_mask:0xf
	v_mul_f32_dpp v171, v11, v211 row_ror:1 row_mask:0xf bank_mask:0xf
	v_mul_f32_dpp v129, v75, v199 row_ror:2 row_mask:0xf bank_mask:0xf
	v_mul_f32_dpp v175, v11, v203 row_ror:2 row_mask:0xf bank_mask:0xf
	v_pk_fma_f32 v[118:119], v[212:213], v[68:69], v[220:221]
	v_pk_fma_f32 v[164:165], v[216:217], v[4:5], v[224:225]
	v_pk_fma_f32 v[120:121], v[214:215], v[70:71], v[222:223]
	v_pk_fma_f32 v[166:167], v[218:219], v[6:7], v[226:227]
	v_mul_f32_dpp v122, v68, v204 row_shr:1 row_mask:0xf bank_mask:0xf
	v_mul_f32_dpp v168, v4, v208 row_shr:1 row_mask:0xf bank_mask:0xf
	v_mul_f32_dpp v126, v68, v196 row_shr:2 row_mask:0xf bank_mask:0xf
	v_mul_f32_dpp v172, v4, v200 row_shr:2 row_mask:0xf bank_mask:0xf
	v_mul_f32_dpp v123, v69, v205 row_shr:1 row_mask:0xf bank_mask:0xf
	v_mul_f32_dpp v169, v5, v209 row_shr:1 row_mask:0xf bank_mask:0xf
	v_mul_f32_dpp v127, v69, v197 row_shr:2 row_mask:0xf bank_mask:0xf
	v_mul_f32_dpp v173, v5, v201 row_shr:2 row_mask:0xf bank_mask:0xf
	v_mul_f32_dpp v124, v70, v206 row_shr:1 row_mask:0xf bank_mask:0xf
	v_mul_f32_dpp v170, v6, v210 row_shr:1 row_mask:0xf bank_mask:0xf
	v_mul_f32_dpp v128, v70, v198 row_shr:2 row_mask:0xf bank_mask:0xf
	v_mul_f32_dpp v174, v6, v202 row_shr:2 row_mask:0xf bank_mask:0xf
	v_mul_f32_dpp v125, v71, v207 row_shr:1 row_mask:0xf bank_mask:0xf
	v_mul_f32_dpp v171, v7, v211 row_shr:1 row_mask:0xf bank_mask:0xf
	v_mul_f32_dpp v129, v71, v199 row_shr:2 row_mask:0xf bank_mask:0xf
	v_mul_f32_dpp v175, v7, v203 row_shr:2 row_mask:0xf bank_mask:0xf
	v_pk_add_f32 v[118:119], v[118:119], v[122:123]
	v_pk_add_f32 v[164:165], v[164:165], v[168:169]
	v_pk_add_f32 v[120:121], v[120:121], v[124:125]
	v_pk_add_f32 v[166:167], v[166:167], v[170:171]
	v_pk_add_f32 v[118:119], v[118:119], v[126:127]
	v_pk_add_f32 v[164:165], v[164:165], v[172:173]
	v_pk_add_f32 v[120:121], v[120:121], v[128:129]
	v_pk_add_f32 v[166:167], v[166:167], v[174:175]
	v_pk_mul_f32 v[122:123], v[118:119], v[118:119]
	v_pk_mul_f32 v[168:169], v[164:165], v[164:165]
	v_pk_mul_f32 v[124:125], v[120:121], v[120:121]
	v_pk_mul_f32 v[170:171], v[166:167], v[166:167]
	v_pk_fma_f32 v[122:123], v[122:123], v[232:233], v[178:179] op_sel_hi:[1,0,0]
	v_pk_fma_f32 v[168:169], v[168:169], v[232:233], v[178:179] op_sel_hi:[1,0,0]
	v_pk_fma_f32 v[124:125], v[124:125], v[232:233], v[178:179] op_sel_hi:[1,0,0]
	v_pk_fma_f32 v[170:171], v[170:171], v[232:233], v[178:179] op_sel_hi:[1,0,0]
	v_pk_mul_f32 v[122:123], v[118:119], v[122:123] neg_lo:[0,1] neg_hi:[0,1]
	v_pk_mul_f32 v[168:169], v[164:165], v[168:169] neg_lo:[0,1] neg_hi:[0,1]
	v_pk_mul_f32 v[124:125], v[120:121], v[124:125] neg_lo:[0,1] neg_hi:[0,1]
	v_pk_mul_f32 v[170:171], v[166:167], v[170:171] neg_lo:[0,1] neg_hi:[0,1]
	v_exp_f32_e32 v126, v122
	v_exp_f32_e32 v172, v168
	v_exp_f32_e32 v127, v123
	v_exp_f32_e32 v173, v169
	v_exp_f32_e32 v128, v124
	v_exp_f32_e32 v174, v170
	v_exp_f32_e32 v129, v125
	v_exp_f32_e32 v175, v171
	v_pk_add_f32 v[126:127], v[126:127], v[248:249] op_sel_hi:[1,0]
	v_pk_add_f32 v[172:173], v[172:173], v[248:249] op_sel_hi:[1,0]
	v_pk_add_f32 v[128:129], v[128:129], v[248:249] op_sel_hi:[1,0]
	v_pk_add_f32 v[174:175], v[174:175], v[248:249] op_sel_hi:[1,0]
	v_rcp_f32_e32 v126, v126
	v_rcp_f32_e32 v172, v172
	v_rcp_f32_e32 v127, v127
	v_rcp_f32_e32 v173, v173
	v_rcp_f32_e32 v128, v128
	v_rcp_f32_e32 v174, v174
	v_rcp_f32_e32 v129, v129
	v_rcp_f32_e32 v175, v175
	v_pk_mul_f32 v[122:123], v[118:119], v[126:127]
	v_pk_mul_f32 v[168:169], v[164:165], v[172:173]
	v_pk_mul_f32 v[124:125], v[120:121], v[128:129]
	v_pk_mul_f32 v[170:171], v[166:167], v[174:175]
	v_pk_mul_f32 v[64:65], v[64:65], v[122:123]
	v_pk_mul_f32 v[0:1], v[0:1], v[168:169]
	v_pk_mul_f32 v[66:67], v[66:67], v[124:125]
	v_pk_mul_f32 v[2:3], v[2:3], v[170:171]
	v_cvt_pk_bf16_f32 v190, v64, v65
	v_cvt_pk_bf16_f32 v192, v0, v1
	v_cvt_pk_bf16_f32 v191, v66, v67
	v_cvt_pk_bf16_f32 v193, v2, v3
	global_store_dwordx4 v[162:163], v[190:193], off
